# layer-1 weight-conversion loop: the 8 serialized gain loads issued together (same fix as the layer-0 loops)
# baseline (speedup 1.0000x reference)
.LBB0_1508:
	v_readlane_b32 s6, v252, 23
	v_readlane_b32 s7, v252, 24
	v_readlane_b32 s48, v250, 26
	v_ashrrev_i32_e32 v5, 31, v4
	v_cndmask_b32_e64 v6, 0, 1, s[6:7]
	v_readlane_b32 s49, v250, 27
	s_waitcnt vmcnt(0)
	v_mul_f32_e32 v7, s31, v39
	v_cmp_ne_u32_e64 s[4:5], 1, v6
	s_andn2_b64 vcc, exec, s[6:7]
	v_readlane_b32 s60, v250, 38
	v_readlane_b32 s61, v250, 39
	v_readlane_b32 s62, v250, 40
	v_readlane_b32 s63, v250, 41
	v_lshl_add_u64 v[4:5], v[4:5], 2, s[48:49]
	v_readlane_b32 s50, v250, 28
	v_readlane_b32 s51, v250, 29
	v_readlane_b32 s52, v250, 30
	v_readlane_b32 s53, v250, 31
	v_readlane_b32 s54, v250, 32
	v_readlane_b32 s55, v250, 33
	v_readlane_b32 s56, v250, 34
	v_readlane_b32 s57, v250, 35
	v_readlane_b32 s58, v250, 36
	v_readlane_b32 s59, v250, 37
	s_cbranch_vccnz .LBB0_1510
	global_load_dword v100, v[4:5], off
	global_load_dword v101, v[4:5], off offset:32
	global_load_dword v102, v[4:5], off offset:64
	global_load_dword v103, v[4:5], off offset:96
	global_load_dword v104, v[4:5], off offset:128
	global_load_dword v105, v[4:5], off offset:160
	global_load_dword v106, v[4:5], off offset:192
	global_load_dword v107, v[4:5], off offset:224
	s_waitcnt vmcnt(0)
	v_mul_f32_e32 v7, v7, v100
.LBB0_1510:
	s_movk_i32 s1, 0x104
	v_lshl_add_u32 v6, v34, 2, 0
	v_mul_lo_u32 v34, v2, s1
	v_readlane_b32 s34, v252, 27
	v_readlane_b32 s36, v252, 33
	v_add_u32_e32 v6, v6, v34
	v_readlane_b32 s35, v252, 28
	v_readlane_b32 s37, v252, 34
	ds_write_b32 v6, v7
	s_and_b64 vcc, exec, s[4:5]
	v_mul_f32_e32 v7, s31, v38
	s_cbranch_vccnz .LBB0_1512
	v_mul_f32_e32 v7, v7, v101
.LBB0_1512:
	ds_write_b32 v6, v7 offset:2080
	s_and_b64 vcc, exec, s[4:5]
	v_mul_f32_e32 v7, s31, v37
	s_cbranch_vccnz .LBB0_1514
	v_mul_f32_e32 v7, v7, v102
.LBB0_1514:
	ds_write_b32 v6, v7 offset:4160
	s_and_b64 vcc, exec, s[4:5]
	v_mul_f32_e32 v7, s31, v36
	s_cbranch_vccnz .LBB0_1516
	v_mul_f32_e32 v7, v7, v103
.LBB0_1516:
	ds_write_b32 v6, v7 offset:6240
	s_and_b64 vcc, exec, s[4:5]
	v_mul_f32_e32 v7, s31, v35
	s_cbranch_vccnz .LBB0_1518
	v_mul_f32_e32 v7, v7, v104
.LBB0_1518:
	ds_write_b32 v6, v7 offset:8320
	s_and_b64 vcc, exec, s[4:5]
	v_mul_f32_e32 v7, s31, v32
	s_cbranch_vccnz .LBB0_1520
	v_mul_f32_e32 v7, v7, v105
.LBB0_1520:
	ds_write_b32 v6, v7 offset:10400
	s_and_b64 vcc, exec, s[4:5]
	v_mul_f32_e32 v7, s31, v31
	s_cbranch_vccnz .LBB0_1522
	v_mul_f32_e32 v7, v7, v106
.LBB0_1522:
	ds_write_b32 v6, v7 offset:12480
	s_and_b64 vcc, exec, s[4:5]
	v_mul_f32_e32 v7, s31, v30
	s_cbranch_vccnz .LBB0_1524
	v_mul_f32_e32 v7, v7, v107
